# SB item prologue: barrier wait leaves the 8 just-issued Q loads outstanding (vmcnt(8)) so the 7-tile staging overlaps their latency
# speedup vs baseline: 1.0104x; 1.0022x over previous
; #define LAS __attribute__((address_space(3)))
; DI f32x16 zero16() { f32x16 z; for (int i = 0; i < 16; ++i) z[i] = 0.f; return z; }
; #define SB_STAGE(KT, BUF) do { _Pragma("unroll") for (int _j = 0; _j < 3; ++_j) { const int _pc = wu + 8 * _j; if (_pc < 18) { \
;         const unsigned _inc = goff[_j] >= (unsigned)OFF_VST ? 128u : 262144u; \
;         __builtin_amdgcn_global_load_lds((const unsigned*)(wsb + (goff[_j] + (unsigned)(KT) * _inc)), (LAS unsigned*)(lds + (BUF) * SB_BUF + _pc * 1024), 16, 0, 0); } } } while (0)
; DI void sb_block2(const Params& p, LAS unsigned char* lds, int bh, int qb2, int tid) {
;     ...
;     bf16x8 qf[2][4];
; #pragma unroll
;     for (int g = 0; g < 2; ++g)
; #pragma unroll
;         for (int ks = 0; ks < 4; ++ks) qf[g][ks] = *(const bf16x8*)(PROJ + (tok0 + q0[g] + r) * 2048 + hd * 64 + ks * 16 + h * 8);
;     unsigned goff[3];
; #pragma unroll
;     for (int j = 0; j < 3; ++j) {
;         const int pc = wu + 8 * j; goff[j] = 0;
;         if (pc < 18) {
;             const int c = (pc < 9 ? pc : pc - 9) * 64 + lane, lr = c / 9; int cc = c - lr * 9; if (cc == 8) cc = 0;
;             if (pc < 9) { const int k32 = lr & 31, key = (lr & 32) + 16 * ((k32 >> 2) & 1) + (k32 & 3) + 4 * (k32 >> 3);
;                 goff[j] = (unsigned)OFF_PROJ + ((unsigned)(b * S_ + key) * 2048u + 512 + hd * 64 + cc * 8) * 2u; }
;             else goff[j] = (unsigned)OFF_VST + ((unsigned)((b * 8 + hd) * 64 + lr) * (unsigned)S_ + cc * 8) * 2u;
;         }
;     }
;     const char* wsb = uptr((const char*)p.ws);
;     ...
;     f32x16 o0[2], o1[2]; float carry[2]; bool done[2];
; #pragma unroll
;     for (int g = 0; g < 2; ++g) { o0[g] = zero16(); o1[g] = zero16(); carry[g] = 1.f; done[g] = false; }
;     const int ktop = 8 * qb2 + 7;
;     LAS int* flags = (LAS int*)(lds + SB_FLAGS);
;     asm volatile("s_waitcnt vmcnt(0)" ::: "memory");
;     __syncthreads();
;     const int nstaged = ktop + 1 < SB_NB ? ktop + 1 : SB_NB;
;     for (int i = 0; i < nstaged; ++i) SB_STAGE(ktop - i, i);
.LBB0_775:
	s_waitcnt vmcnt(8)
	s_lshl_b32 s0, s4, 3
	v_cndmask_b32_e64 v3, 0, 1, s[2:3]
	s_or_b32 s48, s0, 7
	v_cmp_ne_u32_e64 s[4:5], 1, v3
	s_andn2_b64 vcc, exec, s[2:3]
	s_waitcnt vmcnt(8) lgkmcnt(0)
	s_barrier
	s_cbranch_vccnz .LBB0_807
	v_cmp_lt_u32_e32 vcc, s66, v183
	s_lshl_b32 s1, s72, 10
	s_add_i32 m0, s1, 0
	v_cndmask_b32_e64 v3, 18, 7, vcc
	v_lshl_add_u32 v3, s48, v3, v183
	global_load_lds_dwordx4 v3, s[84:85]
	v_cndmask_b32_e64 v3, 0, 1, s[8:9]
	v_cmp_ne_u32_e64 s[6:7], 1, v3
	s_andn2_b64 vcc, exec, s[8:9]
	s_cbranch_vccz .LBB0_808
